# attention two-tile loop back edge rotated (7.11): loop-carried copy hoisted, direct conditional branch back; on top of v45
# baseline (speedup 1.0000x reference)
; #define SWRITE(b, i) do { *(bf16x8*)((char*)V_lds + (b) * SHM_V + vst0) = sr_[i].vs0;          \
;     *(bf16x8*)((char*)V_lds + (b) * SHM_V + vst1) = sr_[i].vs1; int kc = sc * 2;               \
;     *(bf16x8*)((char*)K_lds + (b) * SHM_K + KSWZ(sr, kc)) = sr_[i].ks0;                       \
;     *(bf16x8*)((char*)K_lds + (b) * SHM_K + KSWZ(32 + sr, kc)) = sr_[i].ks1; } while (0)
; #define SWAIT() asm volatile("s_waitcnt vmcnt(4)" ::: "memory")
; #define RESC(a) do { if (__any((a) < 1.f)) { if (hi == 0) al_l[r32] = (a); asm volatile("s_waitcnt lgkmcnt(0)" ::: "memory"); \
;     _Pragma("unroll") for (int d = 0; d < 4; ++d) _Pragma("unroll") for (int r = 0; r < 16; ++r) o[d][r] *= al_l[crow(r, hi)]; } } while (0)
; DI void partialSM(f32x16& p0, f32x16& p1, float& m_reg, float& mn, float& alpha) {
;     ...
;   float mnC = -mn * C;
; #pragma unroll
;   for (int r = 0; r < 16; ++r) p0[r] = fmaf(p0[r], C, mnC);
; #pragma unroll
;   for (int r = 0; r < 16; ++r) p1[r] = fmaf(p1[r], C, mnC);
; #pragma unroll
;   for (int r = 0; r < 16; ++r) p0[r] = __builtin_amdgcn_exp2f(p0[r]);
; DI void attn_dense_body(const bf16_t* __restrict__ Qb, const bf16_t* __restrict__ Kh, const bf16_t* __restrict__ Vh, const bf16_t* SZb, bf16_t* Ub, int seq, char* lds, int wv, const float* qn, int tpos) {
;     ...
;     pv_d0(o, vb0 + (int)SHM_V, pa0, pa1, pa2, pa3); partialSM(pA0, pA1, m_reg, mnA, alA);
;     __syncthreads(); SWAIT(); SWRITE(1, SO);
;     RESC(alA); __syncthreads();
;   }
.LBB0_2011:
	v_cndmask_b32_e64 v164, v161, v218, s[4:5]
	v_mul_f32_e32 v150, 0xbe0293ee, v164
	v_mov_b32_e32 v151, v150
	v_fmamk_f32 v80, v80, 0x3e0293ee, v150
	v_fmamk_f32 v81, v81, 0x3e0293ee, v150
	v_fmamk_f32 v82, v82, 0x3e0293ee, v150
	v_fmamk_f32 v83, v83, 0x3e0293ee, v150
	v_fmamk_f32 v84, v84, 0x3e0293ee, v150
	v_fmamk_f32 v85, v85, 0x3e0293ee, v150
	v_fmamk_f32 v86, v86, 0x3e0293ee, v150
	v_fmamk_f32 v87, v87, 0x3e0293ee, v150
	v_fmamk_f32 v88, v88, 0x3e0293ee, v150
	v_fmamk_f32 v89, v89, 0x3e0293ee, v150
	v_fmamk_f32 v90, v90, 0x3e0293ee, v150
	v_fmamk_f32 v91, v91, 0x3e0293ee, v150
	v_fmamk_f32 v92, v92, 0x3e0293ee, v150
	v_fmamk_f32 v93, v93, 0x3e0293ee, v150
	v_fmamk_f32 v94, v94, 0x3e0293ee, v150
	v_fmac_f32_e32 v151, 0x3e0293ee, v95
	v_exp_f32_e32 v175, v80
	v_exp_f32_e32 v219, v81
	v_exp_f32_e32 v161, v82
	v_exp_f32_e32 v218, v83
	v_exp_f32_e32 v162, v84
	v_exp_f32_e32 v174, v85
	v_exp_f32_e32 v163, v86
	v_exp_f32_e32 v173, v87
	v_exp_f32_e32 v170, v88
	v_exp_f32_e32 v172, v89
	v_exp_f32_e32 v169, v90
	v_exp_f32_e32 v171, v91
	v_exp_f32_e32 v166, v92
	v_exp_f32_e32 v168, v93
	v_exp_f32_e32 v165, v94
	v_exp_f32_e32 v167, v151
	v_pk_fma_f32 v[156:157], v[64:65], s[6:7], v[150:151] op_sel_hi:[1,0,0]
	v_add_f32_e32 v64, v216, v217
	v_fmac_f32_e32 v64, v215, v209
	v_add_f32_e32 v209, v221, v222
	v_pk_fma_f32 v[152:153], v[66:67], s[6:7], v[150:151] op_sel_hi:[1,0,0]
	v_pk_fma_f32 v[148:149], v[68:69], s[6:7], v[150:151] op_sel_hi:[1,0,0]
	v_pk_fma_f32 v[146:147], v[70:71], s[6:7], v[150:151] op_sel_hi:[1,0,0]
	v_pk_fma_f32 v[144:145], v[72:73], s[6:7], v[150:151] op_sel_hi:[1,0,0]
	v_pk_fma_f32 v[158:159], v[74:75], s[6:7], v[150:151] op_sel_hi:[1,0,0]
	v_pk_fma_f32 v[154:155], v[76:77], s[6:7], v[150:151] op_sel_hi:[1,0,0]
	v_pk_fma_f32 v[150:151], v[78:79], s[6:7], v[150:151] op_sel_hi:[1,0,0]
	v_fmac_f32_e32 v209, v64, v220
	s_add_i32 s34, s34, 2
	v_lshl_add_u64 v[184:185], v[184:185], 0, s[66:67]
	s_and_b64 vcc, exec, s[10:11]
	s_waitcnt lgkmcnt(0)
	s_barrier
	v_mov_b32_e32 v215, v160
	s_cbranch_vccz .LBB0_2001
	s_branch .LBB0_2013
